# P3 unit order made batch-local (XCC group x computes batch x); SEAM3 fast path: recurrence workgroups wait only for their XCC, first side workgroup per XCC does the write-back + cross-XCC arrival; cen
# baseline (speedup 1.0000x reference)
; __device__ __forceinline__ unsigned xb_ld(unsigned* p)              { return __hip_atomic_load(p, __ATOMIC_RELAXED, __HIP_MEMORY_SCOPE_AGENT); }
; __device__ __forceinline__ unsigned xb_add(unsigned* p, unsigned v) { return __hip_atomic_fetch_add(p, v, __ATOMIC_RELAXED, __HIP_MEMORY_SCOPE_AGENT); }
; #define XB_SPIN(cond, bar) do { unsigned _sp = 0; while (cond) { __builtin_amdgcn_s_sleep(1); \
;     if ((++_sp & 255u) == 0u) { if (xb_ld(&(bar)[XB_TMO])) break; if (_sp > XB_SPIN_CAP) { atomicAdd(&(bar)[XB_TMO], 1u); break; } } } } while (0)
; __device__ __forceinline__ void xcd_barrier(const XcdBarrier& b) {
;     asm volatile("s_waitcnt vmcnt(0)" ::: "memory");
;     __syncthreads();
;     if (threadIdx.x == 0) {
;         unsigned* bar = b.bar;
;         __builtin_amdgcn_s_waitcnt(0);
;         unsigned nloc = b.st[0], nx = b.st[1];
;         if (nloc == 0u) { xcd_barrier_complete(bar, b.x, nloc, nx); b.st[0] = nloc; b.st[1] = nx; }
;         const unsigned old = xb_add(&bar[XB_XSUB(b.x)], 1u);
;         const unsigned gen = old / nloc;
;         if (old + 1u == (gen + 1u) * nloc) {
;             __builtin_amdgcn_fence(__ATOMIC_RELEASE, "agent");
;             asm volatile("s_waitcnt vmcnt(0)" ::: "memory");
;             const unsigned og = xb_add(&bar[XB_TOP], 1u);
;             const unsigned tg = og / nx;
;             if (og + 1u == (tg + 1u) * nx) xb_add(&bar[XB_TOPGEN], 1u);
;             else XB_SPIN(xb_ld(&bar[XB_TOPGEN]) == tg, bar);
;             __builtin_amdgcn_fence(__ATOMIC_ACQUIRE, "agent");
;             xb_add(&bar[XB_XGEN(b.x)], 1u);
;             asm volatile("s_waitcnt vmcnt(0)" ::: "memory");
;         } else {
;             XB_SPIN(xb_ld(&bar[XB_XGEN(b.x)]) == gen, bar);
;             __builtin_amdgcn_fence(__ATOMIC_ACQUIRE, "agent");
;             asm volatile("s_waitcnt vmcnt(0)" ::: "memory");
;         }
;     }
;     __syncthreads();
; }
.LBB0_193:
	s_or_b64 exec, exec, s[10:11]
	s_waitcnt vmcnt(0)
	s_branch .LBB0_194
.Ls1_other:
	s_mov_b64 exec, s[4:5]
	v_readfirstlane_b32 s6, v188
	s_nop 3
	s_cmp_lg_u32 s6, 64
	s_cbranch_scc1 .LBB0_194
	v_and_b32_e32 v0, 63, v188
	v_lshlrev_b32_e32 v1, 2, v0
	v_add_u32_e32 v1, 0x3a00, v1
	v_readlane_b32 s10, v248, 0
	v_readlane_b32 s11, v248, 1
	v_and_b32_e32 v6, 7, v0
	v_lshlrev_b32_e32 v6, 2, v6
	s_nop 4
	global_load_dword v2, v1, s[10:11] sc1
	global_load_dword v3, v1, s[10:11] offset:256 sc1
	global_load_dword v4, v1, s[10:11] offset:512 sc1
	global_load_dword v5, v1, s[10:11] offset:768 sc1
	s_waitcnt vmcnt(0)
	ds_bpermute_b32 v7, v6, v2
	s_waitcnt lgkmcnt(0)
	v_xor_b32_e32 v2, v2, v7
	v_xor_b32_e32 v3, v3, v7
	v_xor_b32_e32 v4, v4, v7
	v_xor_b32_e32 v5, v5, v7
	v_or3_b32 v2, v2, v3, v4
	v_or_b32_e32 v2, v2, v5
	v_mov_b32_e32 v8, 1
	v_lshlrev_b32_e32 v8, v7, v8
	v_cmp_ne_u32_e32 vcc, 0, v2
	v_cmp_eq_u32_e64 s[6:7], 0, v7
	s_or_b64 s[6:7], vcc, s[6:7]
	v_readlane_b32 s8, v8, 0
	v_readlane_b32 s9, v8, 1
	s_nop 1
	s_or_b32 s8, s8, s9
	v_readlane_b32 s9, v8, 2
	s_nop 1
	s_or_b32 s8, s8, s9
	v_readlane_b32 s9, v8, 3
	s_nop 1
	s_or_b32 s8, s8, s9
	v_readlane_b32 s9, v8, 4
	s_nop 1
	s_or_b32 s8, s8, s9
	v_readlane_b32 s9, v8, 5
	s_nop 1
	s_or_b32 s8, s8, s9
	v_readlane_b32 s9, v8, 6
	s_nop 1
	s_or_b32 s8, s8, s9
	v_readlane_b32 s9, v8, 7
	s_nop 1
	s_or_b32 s8, s8, s9
	s_bcnt1_i32_b32 s8, s8
	s_cmp_eq_u64 s[6:7], 0
	s_cselect_b32 s9, 1, 0
	s_cmp_eq_u32 s8, 8
	s_cselect_b32 s9, s9, 0
	v_mov_b32_e32 v2, s9
	v_mov_b32_e32 v3, 0x27e08
	ds_write_b32 v3, v2
.LBB0_194:
	s_or_b64 exec, exec, s[4:5]
	s_waitcnt lgkmcnt(0)
	s_barrier

; template <class Epi, class Sched, bool ALIGN_EPI = false, bool SP2 = false>
; __device__ __forceinline__ void gemm_phase(PG8_LAS unsigned char* lds, const Gemm g, const Sched& S, const Epi& E) {
;     const int tid = threadIdx.x, wid = __builtin_amdgcn_readfirstlane(tid >> 6), lane = tid & 63, wr = wid >> 2, wc = wid & 3, fr = lane & 15, fq = lane >> 4;
;     const int K = g.K, nt = K / BK;
;     unsigned voffA[2], voffB[2];
; #pragma unroll
;     for (int i = 0; i < 2; ++i) { int R, C; stage_rc(tid * 16 + i * 8192, R, C); const int Rb = Epi::PERM ? ((R & ~31) + perm32(R & 31)) : R;
;         voffA[i] = (unsigned)(R * K + C) * 2u; voffB[i] = (unsigned)(Rb * K + C) * 2u; }
;     const size_t kstep = (size_t)(BK * 2);
;     const size_t hstep = (size_t)HALF * K * 2;
;     const size_t tstep = 2 * hstep;
;     const unsigned ldsw = (unsigned)wid * 1024u;
;     const int aoff = lds_byte(wr * 64 + fr, fq * 8), boff = lds_byte(wc * 32 + fr, fq * 8);
;     ...
;     Unit cur, nxt; int ui = 0;
;     if (!S.next(0, cur)) return;
;     f32x4 acc[2][2][4][2];
; #pragma unroll
;     for (int a = 0; a < 2; ++a)
; #pragma unroll
;         for (int b = 0; b < 2; ++b)
; #pragma unroll
;             for (int m = 0; m < 4; ++m)
; #pragma unroll
;                 for (int n = 0; n < 2; ++n) acc[a][b][m][n] = (f32x4){0.f, 0.f, 0.f, 0.f};
;     bf16x8 At[4][2], B0[2][2], B1[2][2];
;     const char* cA = (const char*)g.A + (size_t)cur.pm * tstep; const char* cB = (const char*)g.Bt + (size_t)cur.pn * tstep;
;     S.a_ready(cur);
;     if constexpr (SP2) {
;         PG8_STAGE(PG8_SB(0, 0), cB, voffB); PG8_STAGE(PG8_SB(0, 1), cB + hstep, voffB); PG8_STAGE(PG8_SA(0, 0), cA, voffA); PG8_STAGE(PG8_SA(0, 1), cA + hstep, voffA);
;         if (wr == 1) PG8_BAR;
;         PG8_WAIT_V(2); PG8_BAR;
;         PG8_STAGE(PG8_SB(1, 0), cB + kstep, voffB); PG8_STAGE(PG8_SA(1, 0), cA + kstep, voffA); PG8_STAGE(PG8_SB(1, 1), cB + hstep + kstep, voffB);
;         PG8_WAIT_V(6); PG8_BAR;
;     } else {
;         PG8_STAGE(PG8_SB(0, 0), cB, voffB); PG8_STAGE(PG8_SA(0, 0), cA, voffA); PG8_STAGE(PG8_SB(0, 1), cB + hstep, voffB); PG8_STAGE(PG8_SA(0, 1), cA + hstep, voffA);
;         if (wr == 1) PG8_BAR;
;         PG8_WAIT_V(4); PG8_BAR;
;         PG8_STAGE(PG8_SB(1, 0), cB + kstep, voffB); PG8_STAGE(PG8_SA(1, 0), cA + kstep, voffA); PG8_STAGE(PG8_SB(1, 1), cB + hstep + kstep, voffB);
.LBB0_317:
	s_add_u32 s98, s78, 0x1f03800
	s_addc_u32 s99, s79, 0
	s_mov_b32 s100, 0
	s_cmp_lt_i32 s82, 4
	s_cselect_b64 s[4:5], -1, 0
	s_and_b64 s[4:5], s[4:5], s[0:1]
	s_andn2_b64 vcc, exec, s[4:5]
	s_cbranch_vccnz .LBB0_350
	s_cmpk_gt_i32 s2, 0x2ff
	v_readfirstlane_b32 s1, v188
	s_cbranch_scc1 .LBB0_350
	s_waitcnt vmcnt(0)
	v_lshrrev_b32_e32 v0, 5, v188
	v_lshrrev_b32_e32 v2, 1, v188
	v_and_b32_e32 v0, 4, v0
	v_bfe_u32 v1, v188, 2, 2
	v_and_b32_e32 v2, 24, v2
	v_or3_b32 v0, v0, v1, v2
	v_lshlrev_b32_e32 v1, 4, v188
	v_add_u32_e32 v8, 0x2000, v1
	v_lshrrev_b32_e32 v2, 7, v8
	s_movk_i32 s0, 0xe0
	v_and_b32_e32 v4, 32, v188
	v_and_or_b32 v3, v2, s0, v0
	v_bitop3_b32 v9, v1, v4, 48 bitop3:0x6c
	v_and_b32_e32 v10, 64, v188
	v_bfe_u32 v11, v188, 2, 4
	s_movk_i32 s0, 0xf0
	v_or_b32_e32 v1, v9, v10
	v_and_or_b32 v2, v2, s0, v11
	s_add_u32 s48, s78, 0x2000000
	v_lshl_or_b32 v130, v2, 11, v1
	v_lshrrev_b32_e32 v2, 3, v188
	s_movk_i32 s0, 0x60
	s_addc_u32 s49, s79, 0
	v_and_or_b32 v0, v2, s0, v0
	s_movk_i32 s0, 0x70
	s_ashr_i32 s51, s2, 31
	v_lshl_or_b32 v132, v0, 11, v1
	v_and_or_b32 v0, v2, s0, v11
	s_lshr_b32 s0, s51, 29
	s_add_i32 s0, s2, s0
	s_lshr_b32 s9, s1, 6
	s_ashr_i32 s6, s0, 3
	s_and_b32 s0, s0, -8
	s_lshr_b32 s8, s1, 8
	s_lshl_b32 s50, s9, 10
	s_sub_i32 s0, s2, s0
	s_cmp_lt_i32 s0, 0
	s_movk_i32 s52, 0x61
	s_cselect_b32 s7, s52, 0x60
	s_mul_i32 s0, s0, s7
	s_add_i32 s0, s0, s6
	s_ashr_i32 s6, s0, 31
	s_lshr_b32 s6, s6, 25
	s_add_i32 s6, s0, s6
	s_ashr_i32 s7, s6, 7
	s_and_b32 s6, s6, 0xffffff80
	s_sub_i32 s6, s0, s6
	s_bfe_i32 s0, s6, 0x80000
	s_bfe_u32 s0, s0, 0x3000c
	s_add_i32 s10, s6, s0
	s_bfe_i32 s0, s10, 0x80000
	s_and_b32 s10, s10, 0xf8
	s_sub_i32 s6, s6, s10
	s_lshl_b32 s7, s7, 3
	s_sext_i32_i8 s6, s6
	s_add_i32 s7, s7, s6
	s_mul_hi_i32 s6, s7, 0x2aaaaaab
	s_lshr_b32 s10, s6, 31
	s_add_i32 s6, s6, s10
	s_lshl_b32 s10, s6, 3
	s_mul_i32 s6, s6, 6
	s_sext_i32_i16 s0, s0
	s_sub_i32 s6, s7, s6
	s_lshr_b32 s0, s0, 3
	s_add_i32 s40, s10, s6
	s_lshr_b32 s6, s2, 3
	s_mul_i32 s0, s6, 43
	s_lshr_b32 s0, s0, 8
	s_mul_i32 s10, s0, 6
	s_sub_i32 s6, s6, s10
	s_and_b32 s10, s2, 7
	s_lshl_b32 s10, s10, 3
	s_add_i32 s40, s10, s6
	s_ashr_i32 s41, s40, 31
	s_bfe_i64 s[10:11], s[0:1], 0x100000
	s_lshl_b64 s[6:7], s[40:41], 19
	s_lshl_b64 s[10:11], s[10:11], 19
	s_add_u32 s44, s78, s10
	s_addc_u32 s45, s79, s11
	s_add_i32 s53, s50, 0
	s_add_i32 m0, s53, 0x10000
	v_lshl_or_b32 v128, v3, 11, v1
	global_load_lds_dwordx4 v132, s[44:45]
	s_add_i32 m0, s53, 0x12000
	s_add_u32 s10, s44, 0x40000
	global_load_lds_dwordx4 v128, s[44:45]
	s_addc_u32 s11, s45, 0
	s_add_i32 m0, s53, 0x14000
	v_lshl_or_b32 v134, v0, 11, v1
	global_load_lds_dwordx4 v132, s[10:11]
	s_add_i32 m0, s53, 0x16000
	s_add_u32 s42, s48, s6
	s_addc_u32 s43, s49, s7
	s_waitcnt lgkmcnt(0)
	s_add_i32 s58, s53, 0x2000
	global_load_lds_dwordx4 v128, s[10:11]
	s_mov_b32 m0, s53
	s_add_u32 s6, s42, 0x40000
	global_load_lds_dwordx4 v134, s[42:43]
	s_mov_b32 m0, s58
	s_addc_u32 s7, s43, 0
	s_add_i32 s59, s53, 0x4000
	global_load_lds_dwordx4 v130, s[42:43]
	s_mov_b32 m0, s59
	s_add_i32 s60, s53, 0x6000
	global_load_lds_dwordx4 v134, s[6:7]
	s_mov_b32 m0, s60
	v_mov_b32_e32 v137, 0
	global_load_lds_dwordx4 v130, s[6:7]
	v_mov_b32_e32 v133, v137
	v_mov_b32_e32 v129, v137
	v_mov_b32_e32 v135, v137
	v_mov_b32_e32 v131, v137
	s_cmp_eq_u32 s8, 1
	s_movk_i32 s61, 0x2000
	s_mov_b32 s62, 0
	v_lshl_add_u64 v[6:7], s[44:45], 0, v[132:133]
	v_lshl_add_u64 v[2:3], s[44:45], 0, v[128:129]
	v_lshl_add_u64 v[0:1], s[42:43], 0, v[134:135]
	s_cselect_b64 s[6:7], -1, 0
	s_cmp_lg_u32 s8, 1
	v_lshl_add_u64 v[4:5], s[42:43], 0, v[130:131]
	s_cbranch_scc1 .LBB0_321
	s_barrier

;     __device__ __forceinline__ bool next(int i, Unit& u) const { const unsigned c = (i < 4) ? ((list >> (8 * i)) & 0xffu) : 0xffu; if (c == 0xffu) return false; u.pm = pm0 + (int)(c & 7u); u.pn = (int)(c >> 3); return true; }
;     __device__ __forceinline__ bool next(int i, Unit& u) const { if (!base.next(i, u)) return false; u.pm = (u.pm / 6) * 8 + (u.pm % 6); return true; }
;     __host__ __device__ bool next(int i, Unit& u) const {
;         const long L = (long)i * G + c; if (L >= nwg) return false;
;         int wgid = (int)L; { const int q = nwg / NXCD, r = nwg % NXCD, xcd = wgid % NXCD, off = wgid / NXCD; wgid = (xcd < r ? xcd * (q + 1) : r * (q + 1) + (xcd - r) * q) + off; }
;         const int nig = WGM * nN, gid = wgid / nig, fm = gid * WGM, gsz = (nM - fm) < WGM ? (nM - fm) : WGM;
;         u.pm = fm + ((wgid % nig) % gsz); u.pn = (wgid % nig) / gsz; return true;
;     }
; template <class Epi, class Sched, bool ALIGN_EPI = false, bool SP2 = false>
; __device__ __forceinline__ void gemm_phase(PG8_LAS unsigned char* lds, const Gemm g, const Sched& S, const Epi& E) {
;     ...
;         const bool has_next = S.next(ui + 1, nxt);
;         const char* nA = has_next ? (const char*)g.A + (size_t)nxt.pm * tstep : cA; const char* nB = has_next ? (const char*)g.Bt + (size_t)nxt.pn * tstep : cB;
.LBB0_324:
	s_add_i32 s62, s62, 1
	s_mul_i32 s0, s62, s70
	s_mul_hi_u32 s1, s62, s71
	s_add_i32 s1, s1, s0
	s_mul_i32 s0, s62, s71
	s_add_u32 s36, s0, s2
	s_addc_u32 s37, s1, s51
	v_cmp_gt_i64_e32 vcc, s[36:37], v[150:151]
	v_cmp_lt_i64_e64 s[0:1], s[36:37], v[148:149]
	s_cbranch_vccnz .LBB0_326
	s_ashr_i32 s30, s36, 31
	s_lshr_b32 s30, s30, 29
	s_add_i32 s30, s36, s30
	s_ashr_i32 s31, s30, 3
	s_and_b32 s30, s30, -8
	s_sub_i32 s30, s36, s30
	s_cmp_lt_i32 s30, 0
	s_cselect_b32 s34, s52, 0x60
	s_mul_i32 s30, s30, s34
	s_add_i32 s30, s30, s31
	s_ashr_i32 s31, s30, 31
	s_lshr_b32 s31, s31, 25
	s_add_i32 s31, s30, s31
	s_ashr_i32 s34, s31, 7
	s_lshl_b32 s34, s34, 3
	s_sub_i32 s35, 48, s34
	s_min_i32 s35, s35, 8
	s_abs_i32 s36, s35
	v_cvt_f32_u32_e32 v0, s36
	s_sub_i32 s38, 0, s36
	s_and_b32 s31, s31, 0xffffff80
	s_sub_i32 s31, s30, s31
	v_rcp_iflag_f32_e32 v0, v0
	s_abs_i32 s30, s31
	s_xor_b32 s37, s31, s35
	s_ashr_i32 s37, s37, 31
	v_mul_f32_e32 v0, 0x4f7ffffe, v0
	v_cvt_u32_f32_e32 v0, v0
	s_nop 0
	v_readfirstlane_b32 s39, v0
	s_mul_i32 s38, s38, s39
	s_mul_hi_u32 s38, s39, s38
	s_add_i32 s39, s39, s38
	s_mul_hi_u32 s38, s30, s39
	s_mul_i32 s39, s38, s36
	s_sub_i32 s30, s30, s39
	s_add_i32 s41, s38, 1
	s_sub_i32 s39, s30, s36
	s_cmp_ge_u32 s30, s36
	s_cselect_b32 s38, s41, s38
	s_cselect_b32 s30, s39, s30
	s_add_i32 s39, s38, 1
	s_cmp_ge_u32 s30, s36
	s_cselect_b32 s30, s39, s38
	s_xor_b32 s30, s30, s37
	s_sub_i32 s30, s30, s37
	s_mul_i32 s35, s30, s35
	s_sub_i32 s31, s31, s35
	s_add_i32 s34, s34, s31
	s_mul_hi_i32 s31, s34, 0x2aaaaaab
	s_lshr_b32 s35, s31, 31
	s_add_i32 s31, s31, s35
	s_lshl_b32 s35, s31, 3
	s_mul_i32 s31, s31, 6
	s_sub_i32 s31, s34, s31
	s_add_i32 s34, s35, s31
	s_lshl_b32 s31, s62, 5
	s_lshr_b32 s35, s2, 3
	s_add_i32 s31, s31, s35
	s_mul_i32 s30, s31, 43
	s_lshr_b32 s30, s30, 8
	s_mul_i32 s35, s30, 6
	s_sub_i32 s31, s31, s35
	s_and_b32 s35, s2, 7
	s_lshl_b32 s35, s35, 3
	s_add_i32 s34, s35, s31

; __device__ __forceinline__ unsigned xb_ld(unsigned* p)              { return __hip_atomic_load(p, __ATOMIC_RELAXED, __HIP_MEMORY_SCOPE_AGENT); }
; __device__ __forceinline__ unsigned xb_add(unsigned* p, unsigned v) { return __hip_atomic_fetch_add(p, v, __ATOMIC_RELAXED, __HIP_MEMORY_SCOPE_AGENT); }
; #define XB_SPIN(cond, bar) do { unsigned _sp = 0; while (cond) { __builtin_amdgcn_s_sleep(1); \
;     if ((++_sp & 255u) == 0u) { if (xb_ld(&(bar)[XB_TMO])) break; if (_sp > XB_SPIN_CAP) { atomicAdd(&(bar)[XB_TMO], 1u); break; } } } } while (0)
; __device__ __forceinline__ void xcd_barrier(const XcdBarrier& b) {
;     asm volatile("s_waitcnt vmcnt(0)" ::: "memory");
;     __syncthreads();
;     if (threadIdx.x == 0) {
;         unsigned* bar = b.bar;
;         __builtin_amdgcn_s_waitcnt(0);
;         unsigned nloc = b.st[0], nx = b.st[1];
;         if (nloc == 0u) { xcd_barrier_complete(bar, b.x, nloc, nx); b.st[0] = nloc; b.st[1] = nx; }
;         const unsigned old = xb_add(&bar[XB_XSUB(b.x)], 1u);
;         const unsigned gen = old / nloc;
;         if (old + 1u == (gen + 1u) * nloc) {
;             __builtin_amdgcn_fence(__ATOMIC_RELEASE, "agent");
;             asm volatile("s_waitcnt vmcnt(0)" ::: "memory");
;             const unsigned og = xb_add(&bar[XB_TOP], 1u);
;             const unsigned tg = og / nx;
;             if (og + 1u == (tg + 1u) * nx) xb_add(&bar[XB_TOPGEN], 1u);
;             else XB_SPIN(xb_ld(&bar[XB_TOPGEN]) == tg, bar);
;             __builtin_amdgcn_fence(__ATOMIC_ACQUIRE, "agent");
;             xb_add(&bar[XB_XGEN(b.x)], 1u);
;             asm volatile("s_waitcnt vmcnt(0)" ::: "memory");
.LBB0_350:
	s_cmp_gt_i32 s83, 4
	s_cselect_b64 s[0:1], -1, 0
	s_and_b64 s[4:5], s[4:5], s[0:1]
	s_andn2_b64 vcc, exec, s[4:5]
	s_cbranch_vccnz .LBB0_404
	s_waitcnt vmcnt(0) lgkmcnt(0)
	s_barrier
	s_mov_b64 s[4:5], exec
	v_readlane_b32 s6, v248, 2
	v_readlane_b32 s7, v248, 3
	s_and_b64 s[6:7], s[4:5], s[6:7]
	s_mov_b64 exec, s[6:7]
	s_cbranch_execz .Ls3_close
	s_add_i32 s6, 0, 0x27e00
	v_mov_b32_e32 v0, s6
	ds_read2_b32 v[2:3], v0 offset1:1
	ds_read_b32 v13, v0 offset:8
	v_readlane_b32 s10, v248, 0
	v_readlane_b32 s11, v248, 1
	s_lshl_b32 s6, s3, 8
	s_nop 1
	s_add_u32 s6, s10, s6
	s_addc_u32 s7, s11, 0
	v_mov_b32_e32 v4, 1
	v_mov_b32_e32 v5, 0x1000
	global_atomic_add v6, v5, v4, s[6:7] offset:1024 sc0
	s_waitcnt vmcnt(0) lgkmcnt(0)
	v_cvt_f32_u32_e32 v7, v2
	v_sub_u32_e32 v8, 0, v2
	v_rcp_iflag_f32_e32 v7, v7
	s_nop 0
	v_mul_f32_e32 v7, 0x4f7ffffe, v7
	v_cvt_u32_f32_e32 v7, v7
	v_mul_lo_u32 v8, v8, v7
	v_mul_hi_u32 v8, v7, v8
	v_add_u32_e32 v7, v7, v8
	v_mul_hi_u32 v7, v6, v7
	v_mul_lo_u32 v8, v7, v2
	v_sub_u32_e32 v8, v6, v8
	v_add_u32_e32 v9, 1, v7
	v_cmp_ge_u32_e32 vcc, v8, v2
	s_nop 1
	v_cndmask_b32_e32 v7, v7, v9, vcc
	v_sub_u32_e32 v9, v8, v2
	v_cndmask_b32_e32 v8, v8, v9, vcc
	v_add_u32_e32 v9, 1, v7
	v_cmp_ge_u32_e32 vcc, v8, v2
	s_nop 1
	v_cndmask_b32_e32 v7, v7, v9, vcc
	v_add_u32_e32 v9, 1, v7
	v_readfirstlane_b32 s98, v7
	v_readfirstlane_b32 s101, v13
	v_mul_lo_u32 v9, v9, v2
	v_add_u32_e32 v10, 1, v6
	v_cmp_eq_u32_e32 vcc, v10, v9
	s_cbranch_vccz .Ls3_notleader
	s_cmp_lg_u32 s101, 0
	s_cbranch_scc1 .Ls3_fleader
	buffer_wbl2 sc1
	s_waitcnt vmcnt(0)
	v_mov_b32_e32 v5, 0x2000
	global_atomic_add v5, v4, s[6:7] offset:1024
	v_mov_b32_e32 v5, 0x3000
	global_atomic_add v11, v5, v4, s[10:11] offset:1024 sc0
	v_add_u32_e32 v9, 1, v7
	v_mul_lo_u32 v9, v9, v3
	s_waitcnt vmcnt(0)
	v_add_u32_e32 v10, 1, v11
	v_cmp_eq_u32_e32 vcc, v10, v9
	s_cbranch_vccz .Ls3_notleader
	global_atomic_add v5, v4, s[10:11] offset:1280
	s_branch .Ls3_notleader

; __device__ __forceinline__ unsigned xb_ld(unsigned* p)              { return __hip_atomic_load(p, __ATOMIC_RELAXED, __HIP_MEMORY_SCOPE_AGENT); }
; __device__ __forceinline__ unsigned xb_add(unsigned* p, unsigned v) { return __hip_atomic_fetch_add(p, v, __ATOMIC_RELAXED, __HIP_MEMORY_SCOPE_AGENT); }
; #define XB_SPIN(cond, bar) do { unsigned _sp = 0; while (cond) { __builtin_amdgcn_s_sleep(1); \
;     if ((++_sp & 255u) == 0u) { if (xb_ld(&(bar)[XB_TMO])) break; if (_sp > XB_SPIN_CAP) { atomicAdd(&(bar)[XB_TMO], 1u); break; } } } } while (0)
; __device__ __forceinline__ void xcd_barrier(const XcdBarrier& b) {
;     ...
;             else XB_SPIN(xb_ld(&bar[XB_TOPGEN]) == tg, bar);
;             __builtin_amdgcn_fence(__ATOMIC_ACQUIRE, "agent");
;             xb_add(&bar[XB_XGEN(b.x)], 1u);
;             asm volatile("s_waitcnt vmcnt(0)" ::: "memory");
;         } else {
;             XB_SPIN(xb_ld(&bar[XB_XGEN(b.x)]) == gen, bar);
;             __builtin_amdgcn_fence(__ATOMIC_ACQUIRE, "agent");
;             asm volatile("s_waitcnt vmcnt(0)" ::: "memory");
;         }
.Ls3_notleader:
	s_cmp_lg_u32 s101, 0
	s_cbranch_scc1 .Ls3_fast
	s_cmp_gt_u32 s2, 63
	s_cbranch_scc1 .Ls3_close
	v_mov_b32_e32 v5, 0x3000
	s_mov_b32 s99, 0

; __device__ __forceinline__ unsigned xb_ld(unsigned* p)              { return __hip_atomic_load(p, __ATOMIC_RELAXED, __HIP_MEMORY_SCOPE_AGENT); }
; __device__ __forceinline__ unsigned xb_add(unsigned* p, unsigned v) { return __hip_atomic_fetch_add(p, v, __ATOMIC_RELAXED, __HIP_MEMORY_SCOPE_AGENT); }
; #define XB_SPIN(cond, bar) do { unsigned _sp = 0; while (cond) { __builtin_amdgcn_s_sleep(1); \
;     if ((++_sp & 255u) == 0u) { if (xb_ld(&(bar)[XB_TMO])) break; if (_sp > XB_SPIN_CAP) { atomicAdd(&(bar)[XB_TMO], 1u); break; } } } } while (0)
; __device__ __forceinline__ void xcd_barrier(const XcdBarrier& b) {
;     ...
;             else XB_SPIN(xb_ld(&bar[XB_TOPGEN]) == tg, bar);
;             __builtin_amdgcn_fence(__ATOMIC_ACQUIRE, "agent");
;             xb_add(&bar[XB_XGEN(b.x)], 1u);
;             asm volatile("s_waitcnt vmcnt(0)" ::: "memory");
;         } else {
;             XB_SPIN(xb_ld(&bar[XB_XGEN(b.x)]) == gen, bar);
;             __builtin_amdgcn_fence(__ATOMIC_ACQUIRE, "agent");
;             asm volatile("s_waitcnt vmcnt(0)" ::: "memory");
;         }
.Ls3_fast:
	s_lshr_b32 s8, s2, 3
	s_cmp_gt_u32 s8, 8
	s_cbranch_scc1 .Ls3_close
	v_mov_b32_e32 v5, 0x2000
	s_mov_b32 s99, 0

; __device__ __forceinline__ unsigned xb_ld(unsigned* p)              { return __hip_atomic_load(p, __ATOMIC_RELAXED, __HIP_MEMORY_SCOPE_AGENT); }
; __device__ __forceinline__ unsigned xb_add(unsigned* p, unsigned v) { return __hip_atomic_fetch_add(p, v, __ATOMIC_RELAXED, __HIP_MEMORY_SCOPE_AGENT); }
; #define XB_SPIN(cond, bar) do { unsigned _sp = 0; while (cond) { __builtin_amdgcn_s_sleep(1); \
;     if ((++_sp & 255u) == 0u) { if (xb_ld(&(bar)[XB_TMO])) break; if (_sp > XB_SPIN_CAP) { atomicAdd(&(bar)[XB_TMO], 1u); break; } } } } while (0)
; __device__ __forceinline__ void xcd_barrier(const XcdBarrier& b) {
;     ...
;         const unsigned old = xb_add(&bar[XB_XSUB(b.x)], 1u);
;         const unsigned gen = old / nloc;
;         if (old + 1u == (gen + 1u) * nloc) {
;             __builtin_amdgcn_fence(__ATOMIC_RELEASE, "agent");
;             asm volatile("s_waitcnt vmcnt(0)" ::: "memory");
;             const unsigned og = xb_add(&bar[XB_TOP], 1u);
;             const unsigned tg = og / nx;
;             if (og + 1u == (tg + 1u) * nx) xb_add(&bar[XB_TOPGEN], 1u);
;             else XB_SPIN(xb_ld(&bar[XB_TOPGEN]) == tg, bar);
;             __builtin_amdgcn_fence(__ATOMIC_ACQUIRE, "agent");
;             xb_add(&bar[XB_XGEN(b.x)], 1u);
;             asm volatile("s_waitcnt vmcnt(0)" ::: "memory");
.Ls3_fgo:
	s_cmp_lt_u32 s8, 8
	s_cbranch_scc1 .Ls3_released
	buffer_wbl2 sc1
	s_waitcnt vmcnt(0)
	v_mov_b32_e32 v5, 0x3000
	global_atomic_add v11, v5, v4, s[10:11] offset:1024 sc0
	v_add_u32_e32 v9, 1, v7
	v_lshlrev_b32_e32 v9, 3, v9
	s_waitcnt vmcnt(0)
	v_add_u32_e32 v10, 1, v11
	v_cmp_eq_u32_e32 vcc, v10, v9
	s_cbranch_vccz .Ls3_close
	global_atomic_add v5, v4, s[10:11] offset:1280
